# attention V operand via ds_read_b64_tr_b16 hardware transpose reads from a row-major [8-key][32-col] subtile image: 2 ds_write_b128 replace 16 bank-conflicted ds_write_b16 per thread per tile
# speedup vs baseline: 1.0790x; 1.0074x over previous
.LBB0_337:
	s_andn2_b64 vcc, exec, s[44:45]
	s_cbranch_vccnz .LBB0_447
	v_readlane_b32 s38, v254, 28
	v_readlane_b32 s46, v253, 2
	v_readlane_b32 s39, v254, 29
	v_readlane_b32 s47, v253, 3
	v_mov_b32_e32 v0, v133
	s_andn2_b64 vcc, exec, s[38:39]
	s_cbranch_vccnz .LBB0_384
	v_ashrrev_i32_e32 v4, 3, v0
	v_ashrrev_i32_e32 v5, 31, v4
	s_load_dwordx2 s[44:45], s[46:47], 0xf8
	s_nop 0
	s_load_dwordx2 s[46:47], s[46:47], 0xc0
	v_lshlrev_b64 v[6:7], 8, v[4:5]
	v_lshlrev_b32_e32 v5, 3, v0
	v_and_b32_e32 v8, 56, v5
	v_add_u32_e32 v5, 0x100, v0
	v_ashrrev_i32_e32 v10, 3, v5
	v_bfe_u32 v3, v0, 5, 1
	v_ashrrev_i32_e32 v11, 31, v10
	v_and_b32_e32 v14, 64, v188
	s_waitcnt lgkmcnt(0)
	s_add_u32 s48, s44, 0x22600000
	v_cmp_eq_u32_e32 vcc, 0, v3
	v_lshlrev_b64 v[12:13], 8, v[10:11]
	v_xor_b32_e32 v11, 32, v188
	v_add_u32_e32 v14, 64, v14
	v_ashrrev_i32_e32 v2, 1, v0
	s_addc_u32 s49, s45, 0
	s_movk_i32 s3, 0xffe0
	v_cndmask_b32_e64 v107, 0, 1.0, vcc
	v_and_b32_e32 v5, 7, v0
	v_cmp_lt_i32_e32 vcc, v11, v14
	v_readlane_b32 s38, v254, 60
	v_and_b32_e32 v1, 31, v0
	s_add_u32 s50, s44, 0x31600000
	v_bfi_b32 v106, s3, v2, v0
	v_lshlrev_b32_e32 v2, 3, v3
	v_lshlrev_b32_e32 v9, 4, v5
	s_waitcnt vmcnt(0)
	v_lshlrev_b32_e32 v108, 4, v3
	v_cndmask_b32_e32 v11, v188, v11, vcc
	s_movk_i32 s3, 0x470
	v_readlane_b32 s39, v254, 61
	s_addc_u32 s51, s45, 0
	v_lshlrev_b32_e32 v0, 2, v3
	v_sub_u32_e32 v3, v108, v2
	v_lshlrev_b32_e32 v109, 2, v11
	v_mul_lo_u32 v11, v4, s85
	v_lshlrev_b32_e32 v4, 1, v4
	v_mad_u32_u24 v5, v5, s3, v9
	v_mul_lo_u32 v14, v10, s85
	v_lshlrev_b32_e32 v10, 1, v10
	v_mul_u32_u24_e32 v110, 0x90, v1
	s_lshl_b32 s3, s38, 4
	s_lshl_b32 s52, s38, 17
	v_readlane_b32 s38, v253, 0
	s_mov_b32 s53, s81
	v_or_b32_e32 v111, 0x80, v0
	v_lshlrev_b32_e32 v96, 1, v2
	v_lshlrev_b32_e32 v128, 1, v8
	v_add_u32_e32 v112, v9, v11
	v_add_u32_e32 v113, v5, v4
	v_add_u32_e32 v114, v9, v14
	v_add_u32_e32 v115, v5, v10
	v_add_u32_e32 v116, v3, v110
	v_lshrrev_b32_e32 v168, 6, v133
	v_mul_u32_u24_e32 v166, 0x480, v168
	v_bfe_u32 v168, v133, 3, 3
	v_lshl_add_u32 v166, v168, 6, v166
	v_bfe_u32 v168, v133, 2, 1
	v_mul_u32_u24_e32 v168, 0x240, v168
	v_add_u32_e32 v166, v166, v168
	v_and_b32_e32 v168, 3, v133
	v_lshl_add_u32 v166, v168, 4, v166
	v_bfe_u32 v168, v133, 5, 1
	v_lshlrev_b32_e32 v167, 8, v168
	v_bfe_u32 v168, v133, 2, 2
	v_lshl_add_u32 v167, v168, 6, v167
	v_bfe_u32 v168, v133, 4, 1
	v_lshl_add_u32 v167, v168, 5, v167
	v_and_b32_e32 v168, 3, v133
	v_lshl_add_u32 v167, v168, 3, v167
	v_lshlrev_b32_e32 v98, 1, v0
	v_lshlrev_b64 v[100:101], 1, v[6:7]
	v_lshlrev_b64 v[102:103], 1, v[12:13]
	s_mov_b32 s31, s38
	v_readlane_b32 s39, v253, 1
	s_branch .LBB0_341

.LBB0_368:
	s_add_i32 s94, s96, 1
	s_cmp_ge_u32 s94, s78
	s_barrier
	s_waitcnt vmcnt(3)
	ds_write_b128 v112, v[64:67]
	s_waitcnt vmcnt(2)
	ds_write_b128 v166, v[68:71] offset:9216
	s_waitcnt vmcnt(1)
	ds_write_b128 v114, v[80:83]
	s_waitcnt vmcnt(0)
	ds_write_b128 v166, v[88:91] offset:13824
	s_waitcnt lgkmcnt(0)
	s_barrier
	s_cbranch_scc1 .LBB0_379
	s_and_b64 vcc, exec, s[56:57]
	s_cbranch_vccz .LBB0_371
	s_lshl_b64 s[66:67], s[80:81], 8
	s_add_u32 s66, s66, s58
	s_addc_u32 s67, s67, s59
	s_mov_b64 s[72:73], -1
	s_cbranch_execz .LBB0_372
	s_branch .LBB0_376

.LBB0_379:
	v_add_u32_e32 v122, v108, v110
	ds_read_b128 v[32:35], v122
	ds_read_b128 v[36:39], v122 offset:32
	v_add_u32_e32 v127, s95, v97
	v_cmp_gt_u32_e32 vcc, s9, v127
	s_waitcnt lgkmcnt(1)
	v_mfma_f32_32x32x16_bf16 v[48:63], v[32:35], v[72:75], 0
	ds_read_b128 v[32:35], v122 offset:64
	ds_read_b128 v[118:121], v122 offset:4640
	s_waitcnt lgkmcnt(2)
	v_mfma_f32_32x32x16_bf16 v[48:63], v[36:39], v[76:79], v[48:63]
	s_waitcnt lgkmcnt(1)
	v_mfma_f32_32x32x16_bf16 v[48:63], v[32:35], v[84:87], v[48:63]
	ds_read_b128 v[32:35], v122 offset:96
	s_waitcnt lgkmcnt(0)
	v_mfma_f32_32x32x16_bf16 v[48:63], v[32:35], v[92:95], v[48:63]
	ds_read_b128 v[32:35], v122 offset:4608
	s_waitcnt lgkmcnt(0)
	v_mfma_f32_32x32x16_bf16 v[32:47], v[32:35], v[72:75], 0
	v_mfma_f32_32x32x16_bf16 v[32:47], v[118:121], v[76:79], v[32:47]
	ds_read_b128 v[118:121], v122 offset:4672
	s_waitcnt lgkmcnt(0)
	v_mfma_f32_32x32x16_bf16 v[32:47], v[118:121], v[84:87], v[32:47]
	ds_read_b128 v[118:121], v122 offset:4704
	s_waitcnt lgkmcnt(0)
	v_mfma_f32_32x32x16_bf16 v[32:47], v[118:121], v[92:95], v[32:47]
	ds_read_b64_tr_b16 v[134:135], v167 offset:9216
	ds_read_b64_tr_b16 v[136:137], v167 offset:10368
	ds_read_b64_tr_b16 v[138:139], v167 offset:9792
	ds_read_b64_tr_b16 v[140:141], v167 offset:10944
	ds_read_b64_tr_b16 v[142:143], v167 offset:11520
	ds_read_b64_tr_b16 v[144:145], v167 offset:12672
	ds_read_b64_tr_b16 v[146:147], v167 offset:12096
	ds_read_b64_tr_b16 v[148:149], v167 offset:13248
	ds_read_b64_tr_b16 v[150:151], v167 offset:13824
	ds_read_b64_tr_b16 v[152:153], v167 offset:14976
	ds_read_b64_tr_b16 v[154:155], v167 offset:14400
	ds_read_b64_tr_b16 v[156:157], v167 offset:15552
	ds_read_b64_tr_b16 v[158:159], v167 offset:16128
	ds_read_b64_tr_b16 v[160:161], v167 offset:17280
	ds_read_b64_tr_b16 v[162:163], v167 offset:16704
	ds_read_b64_tr_b16 v[164:165], v167 offset:17856
	s_cmp_eq_u64 s[64:65], 0
	s_cbranch_scc1 .Lattn_nomask
	s_nop 1
	v_cndmask_b32_e32 v118, v189, v48, vcc
	v_cndmask_b32_e64 v48, v48, v118, s[64:65]
	v_add_u32_e32 v118, 1, v127
	v_cmp_gt_u32_e32 vcc, s9, v118
	s_nop 1
	v_cndmask_b32_e32 v118, v189, v49, vcc
	v_cndmask_b32_e64 v49, v49, v118, s[64:65]
	v_add_u32_e32 v118, 2, v127
	v_cmp_gt_u32_e32 vcc, s9, v118
	v_max3_f32 v119, v117, v48, v49
	s_nop 0
	v_cndmask_b32_e32 v118, v189, v50, vcc
	v_cndmask_b32_e64 v50, v50, v118, s[64:65]
	v_add_u32_e32 v118, 3, v127
	v_cmp_gt_u32_e32 vcc, s9, v118
	s_nop 1
	v_cndmask_b32_e32 v118, v189, v51, vcc
	v_cndmask_b32_e64 v118, v51, v118, s[64:65]
	v_max3_f32 v51, v119, v50, v118
	v_add_u32_e32 v119, 8, v127
	v_cmp_gt_u32_e32 vcc, s9, v119
	s_nop 1
	v_cndmask_b32_e32 v119, v189, v52, vcc
	v_cndmask_b32_e64 v52, v52, v119, s[64:65]
	v_add_u32_e32 v119, 9, v127
	v_cmp_gt_u32_e32 vcc, s9, v119
	s_nop 1
	v_cndmask_b32_e32 v119, v189, v53, vcc
	v_cndmask_b32_e64 v53, v53, v119, s[64:65]
	v_add_u32_e32 v119, 10, v127
	v_cmp_gt_u32_e32 vcc, s9, v119
	v_max3_f32 v51, v51, v52, v53
	s_nop 0
	v_cndmask_b32_e32 v119, v189, v54, vcc
	v_cndmask_b32_e64 v54, v54, v119, s[64:65]
	v_add_u32_e32 v119, 11, v127
	v_cmp_gt_u32_e32 vcc, s9, v119
	s_nop 1
	v_cndmask_b32_e32 v119, v189, v55, vcc
	v_cndmask_b32_e64 v119, v55, v119, s[64:65]
	v_add_u32_e32 v55, 16, v127
	v_cmp_gt_u32_e32 vcc, s9, v55
	v_max3_f32 v51, v51, v54, v119
	s_nop 0
	v_cndmask_b32_e32 v55, v189, v56, vcc
	v_cndmask_b32_e64 v121, v56, v55, s[64:65]
	v_add_u32_e32 v55, 17, v127
	v_cmp_gt_u32_e32 vcc, s9, v55
	s_nop 1
	v_cndmask_b32_e32 v55, v189, v57, vcc
	v_cndmask_b32_e64 v120, v57, v55, s[64:65]
	v_add_u32_e32 v55, 18, v127
	v_cmp_gt_u32_e32 vcc, s9, v55
	v_max3_f32 v51, v51, v121, v120
	s_nop 0
	v_cndmask_b32_e32 v55, v189, v58, vcc
	v_cndmask_b32_e64 v122, v58, v55, s[64:65]
	v_add_u32_e32 v55, 19, v127
	v_cmp_gt_u32_e32 vcc, s9, v55
	s_nop 1
	v_cndmask_b32_e32 v55, v189, v59, vcc
	v_cndmask_b32_e64 v123, v59, v55, s[64:65]
	v_add_u32_e32 v55, 24, v127
	v_cmp_gt_u32_e32 vcc, s9, v55
	v_max3_f32 v51, v51, v122, v123
	s_nop 0
	v_cndmask_b32_e32 v55, v189, v60, vcc
	v_cndmask_b32_e64 v60, v60, v55, s[64:65]
	v_add_u32_e32 v55, 25, v127
	v_cmp_gt_u32_e32 vcc, s9, v55
	s_nop 1
	v_cndmask_b32_e32 v55, v189, v61, vcc
	v_cndmask_b32_e64 v61, v61, v55, s[64:65]
	v_add_u32_e32 v55, 26, v127
	v_cmp_gt_u32_e32 vcc, s9, v55
	v_max3_f32 v51, v51, v60, v61
	s_nop 0
	v_cndmask_b32_e32 v55, v189, v62, vcc
	v_cndmask_b32_e64 v62, v62, v55, s[64:65]
	v_add_u32_e32 v55, 27, v127
	v_cmp_gt_u32_e32 vcc, s9, v55
	s_nop 1
	v_cndmask_b32_e32 v55, v189, v63, vcc
	v_cndmask_b32_e64 v63, v63, v55, s[64:65]
	v_add_u32_e32 v55, 32, v127
	v_cmp_gt_u32_e32 vcc, s9, v55
	v_max3_f32 v51, v51, v62, v63
	s_nop 0
	v_cndmask_b32_e32 v55, v189, v32, vcc
	v_cndmask_b32_e64 v124, v32, v55, s[64:65]
	v_add_u32_e32 v32, 33, v127
	v_cmp_gt_u32_e32 vcc, s9, v32
	s_nop 1
	v_cndmask_b32_e32 v32, v189, v33, vcc
	v_cndmask_b32_e64 v125, v33, v32, s[64:65]
	v_add_u32_e32 v33, 34, v127
	v_cmp_gt_u32_e32 vcc, s9, v33
	v_max3_f32 v32, v51, v124, v125
	s_nop 0
	v_cndmask_b32_e32 v33, v189, v34, vcc
	v_cndmask_b32_e64 v126, v34, v33, s[64:65]
	v_add_u32_e32 v33, 35, v127
	v_cmp_gt_u32_e32 vcc, s9, v33
	v_add_u32_e32 v34, 57, v127
	s_nop 0
	v_cndmask_b32_e32 v33, v189, v35, vcc
	v_cndmask_b32_e64 v59, v35, v33, s[64:65]
	v_add_u32_e32 v33, 40, v127
	v_cmp_gt_u32_e32 vcc, s9, v33
	v_max3_f32 v32, v32, v126, v59
	s_nop 0
	v_cndmask_b32_e32 v33, v189, v36, vcc
	v_cndmask_b32_e64 v56, v36, v33, s[64:65]
	v_add_u32_e32 v33, 41, v127
	v_cmp_gt_u32_e32 vcc, s9, v33
	s_nop 1
	v_cndmask_b32_e32 v33, v189, v37, vcc
	v_cndmask_b32_e64 v57, v37, v33, s[64:65]
	v_add_u32_e32 v33, 42, v127
	v_cmp_gt_u32_e32 vcc, s9, v33
	v_max3_f32 v32, v32, v56, v57
	s_nop 0
	v_cndmask_b32_e32 v33, v189, v38, vcc
	v_cndmask_b32_e64 v58, v38, v33, s[64:65]
	v_add_u32_e32 v33, 43, v127
	v_cmp_gt_u32_e32 vcc, s9, v33
	s_nop 1
	v_cndmask_b32_e32 v33, v189, v39, vcc
	v_cndmask_b32_e64 v55, v39, v33, s[64:65]
	v_add_u32_e32 v33, 48, v127
	v_cmp_gt_u32_e32 vcc, s9, v33
	v_max3_f32 v32, v32, v58, v55
	s_nop 0
	v_cndmask_b32_e32 v33, v189, v40, vcc
	v_cndmask_b32_e64 v37, v40, v33, s[64:65]
	v_add_u32_e32 v33, 49, v127
	v_cmp_gt_u32_e32 vcc, s9, v33
	s_nop 1
	v_cndmask_b32_e32 v33, v189, v41, vcc
	v_cndmask_b32_e64 v38, v41, v33, s[64:65]
	v_add_u32_e32 v33, 50, v127
	v_cmp_gt_u32_e32 vcc, s9, v33
	v_max3_f32 v32, v32, v37, v38
	s_nop 0
	v_cndmask_b32_e32 v33, v189, v42, vcc
	v_cndmask_b32_e64 v39, v42, v33, s[64:65]
	v_add_u32_e32 v33, 51, v127
	v_cmp_gt_u32_e32 vcc, s9, v33
	s_nop 1
	v_cndmask_b32_e32 v33, v189, v43, vcc
	v_cndmask_b32_e64 v36, v43, v33, s[64:65]
	v_add_u32_e32 v33, 56, v127
	v_cmp_gt_u32_e32 vcc, s9, v33
	v_max3_f32 v32, v32, v39, v36
	s_nop 0
	v_cndmask_b32_e32 v33, v189, v44, vcc
	v_cmp_gt_u32_e32 vcc, s9, v34
	v_cndmask_b32_e64 v33, v44, v33, s[64:65]
	s_nop 0
	v_cndmask_b32_e32 v34, v189, v45, vcc
	v_cndmask_b32_e64 v34, v45, v34, s[64:65]
	v_max3_f32 v40, v32, v33, v34
	v_add_u32_e32 v32, 58, v127
	v_cmp_gt_u32_e32 vcc, s9, v32
	s_nop 1
	v_cndmask_b32_e32 v32, v189, v46, vcc
	v_cndmask_b32_e64 v35, v46, v32, s[64:65]
	v_add_u32_e32 v32, 59, v127
	v_cmp_gt_u32_e32 vcc, s9, v32
	s_nop 1
	v_cndmask_b32_e32 v32, v189, v47, vcc
	v_cndmask_b32_e64 v32, v47, v32, s[64:65]
	v_max3_f32 v40, v40, v35, v32

.LBB0_381:
	v_sub_f32_e32 v40, v48, v51
	v_exp_f32_e32 v44, v40
	v_sub_f32_e32 v40, v49, v51
	v_sub_f32_e32 v41, v50, v51
	v_exp_f32_e32 v45, v40
	v_exp_f32_e32 v46, v41
	v_sub_f32_e32 v41, v118, v51
	v_exp_f32_e32 v47, v41
	v_sub_f32_e32 v41, v52, v51
	v_add_f32_e32 v40, v44, v99
	v_exp_f32_e32 v48, v41
	v_sub_f32_e32 v41, v53, v51
	v_add_f32_e32 v40, v45, v40
	v_exp_f32_e32 v49, v41
	v_sub_f32_e32 v41, v54, v51
	v_add_f32_e32 v40, v46, v40
	v_exp_f32_e32 v50, v41
	v_sub_f32_e32 v41, v119, v51
	v_add_f32_e32 v40, v47, v40
	v_exp_f32_e32 v52, v41
	v_sub_f32_e32 v41, v121, v51
	v_add_f32_e32 v40, v48, v40
	v_exp_f32_e32 v53, v41
	v_add_f32_e32 v40, v49, v40
	v_add_f32_e32 v40, v50, v40
	v_add_f32_e32 v40, v52, v40
	v_add_f32_e32 v99, v53, v40
	v_sub_f32_e32 v40, v120, v51
	v_exp_f32_e32 v117, v40
	v_sub_f32_e32 v40, v122, v51
	v_exp_f32_e32 v118, v40
	v_sub_f32_e32 v40, v123, v51
	v_exp_f32_e32 v119, v40
	v_sub_f32_e32 v40, v60, v51
	v_exp_f32_e32 v120, v40
	v_sub_f32_e32 v40, v61, v51
	v_exp_f32_e32 v121, v40
	v_sub_f32_e32 v40, v62, v51
	v_exp_f32_e32 v122, v40
	v_sub_f32_e32 v40, v63, v51
	v_exp_f32_e32 v123, v40
	v_sub_f32_e32 v40, v124, v51
	v_exp_f32_e32 v124, v40
	v_sub_f32_e32 v40, v125, v51
	v_exp_f32_e32 v125, v40
	v_sub_f32_e32 v40, v126, v51
	s_nop 0
	v_exp_f32_e32 v126, v40
	s_nop 0
	v_cvt_pk_bf16_f32 v44, v44, v45
	v_cvt_pk_bf16_f32 v45, v46, v47
	v_cvt_pk_bf16_f32 v46, v48, v49
	v_cvt_pk_bf16_f32 v47, v50, v52
	s_nop 0
	s_nop 0
	s_waitcnt lgkmcnt(1)
	v_mfma_f32_32x32x16_bf16 v[16:31], v[134:137], v[44:47], v[16:31]
	v_sub_f32_e32 v40, v56, v51
	v_exp_f32_e32 v56, v40
	v_sub_f32_e32 v40, v57, v51
	v_exp_f32_e32 v57, v40
	v_sub_f32_e32 v40, v58, v51
	v_exp_f32_e32 v58, v40
	s_nop 0
	v_sub_f32_e32 v54, v59, v51
	s_waitcnt lgkmcnt(1)
	v_mfma_f32_32x32x16_bf16 v[0:15], v[138:141], v[44:47], v[0:15]
	v_sub_f32_e32 v44, v55, v51
	v_exp_f32_e32 v59, v54
	v_exp_f32_e32 v60, v44
	v_cvt_pk_bf16_f32 v44, v53, v117
	s_nop 0
	v_sub_f32_e32 v37, v37, v51
	v_cvt_pk_bf16_f32 v45, v118, v119
	v_cvt_pk_bf16_f32 v46, v120, v121
	v_cvt_pk_bf16_f32 v47, v122, v123
	v_exp_f32_e32 v61, v37
	v_sub_f32_e32 v37, v38, v51
	s_waitcnt lgkmcnt(1)
	v_mfma_f32_32x32x16_bf16 v[16:31], v[142:145], v[44:47], v[16:31]
	v_exp_f32_e32 v62, v37
	v_sub_f32_e32 v37, v39, v51
	s_nop 0
	v_sub_f32_e32 v34, v34, v51
	v_sub_f32_e32 v36, v36, v51
	v_exp_f32_e32 v63, v37
	v_cvt_pk_bf16_f32 v42, v124, v125
	s_waitcnt lgkmcnt(1)
	v_mfma_f32_32x32x16_bf16 v[0:15], v[146:149], v[44:47], v[0:15]
	v_exp_f32_e32 v53, v34
	v_sub_f32_e32 v34, v35, v51
	v_exp_f32_e32 v52, v36
	v_cvt_pk_bf16_f32 v43, v126, v59
	v_cvt_pk_bf16_f32 v44, v56, v57
	v_cvt_pk_bf16_f32 v45, v58, v60
	v_exp_f32_e32 v54, v34
	s_nop 0
	s_waitcnt lgkmcnt(1)
	v_mfma_f32_32x32x16_bf16 v[16:31], v[150:153], v[42:45], v[16:31]
	v_sub_f32_e32 v33, v33, v51
	v_sub_f32_e32 v32, v32, v51
	v_exp_f32_e32 v33, v33
	v_exp_f32_e32 v32, v32
	s_nop 0
	v_cvt_pk_bf16_f32 v38, v61, v62
	v_cvt_pk_bf16_f32 v39, v63, v52
	v_cvt_pk_bf16_f32 v40, v33, v53
	v_cvt_pk_bf16_f32 v41, v54, v32
	s_waitcnt lgkmcnt(0)
	v_mfma_f32_32x32x16_bf16 v[0:15], v[154:157], v[42:45], v[0:15]
	s_nop 0
	v_mfma_f32_32x32x16_bf16 v[16:31], v[158:161], v[38:41], v[16:31]
	v_add_f32_e32 v34, v117, v99
	v_add_f32_e32 v34, v118, v34
	v_add_f32_e32 v34, v119, v34
	v_add_f32_e32 v34, v120, v34
	v_add_f32_e32 v34, v121, v34
	v_add_f32_e32 v34, v122, v34
	v_add_f32_e32 v34, v123, v34
	v_add_f32_e32 v34, v124, v34
	v_add_f32_e32 v34, v125, v34
	v_add_f32_e32 v34, v126, v34
	v_add_f32_e32 v34, v59, v34
	v_add_f32_e32 v34, v56, v34
	v_add_f32_e32 v34, v57, v34
	v_add_f32_e32 v34, v58, v34
	v_add_f32_e32 v34, v60, v34
	s_waitcnt lgkmcnt(0)
	v_mfma_f32_32x32x16_bf16 v[0:15], v[162:165], v[38:41], v[0:15]
	v_add_f32_e32 v34, v61, v34
	v_add_f32_e32 v34, v62, v34
	v_add_f32_e32 v34, v63, v34
	v_add_f32_e32 v34, v52, v34
	v_add_f32_e32 v33, v33, v34
	v_add_f32_e32 v33, v53, v33
	v_add_f32_e32 v33, v54, v33
	v_add_f32_e32 v99, v32, v33
	s_add_i32 s80, s80, 64
	s_addk_i32 s93, 0x4000
	s_cmp_eq_u32 s78, s94
	s_cbranch_scc0 .LBB0_348
	s_branch .LBB0_340
